# phase-1 RMSNorm row loop: all shift/scale vectors of both rows loaded up front (dead VGPRs) instead of 7 serialized load->wait->store steps
# speedup vs baseline: 1.0161x; 1.0014x over previous
.LBB0_139:
	v_ashrrev_i32_e32 v67, 31, v66
	v_add_u32_e32 v62, s28, v66
	v_lshlrev_b64 v[18:19], 12, v[66:67]
	v_cmp_gt_i32_e64 s[0:1], s3, v62
	v_lshl_add_u64 v[18:19], v[56:57], 0, v[18:19]
	global_load_dwordx4 v[46:49], v[18:19], off
	global_load_dwordx4 v[38:41], v[18:19], off offset:1024
	global_load_dwordx4 v[22:25], v[18:19], off offset:3072
	global_load_dwordx4 v[30:33], v[18:19], off offset:2048
	v_cndmask_b32_e64 v68, v66, v62, s[0:1]
	v_ashrrev_i32_e32 v69, 31, v68
	v_lshlrev_b64 v[18:19], 12, v[68:69]
	v_lshl_add_u64 v[64:65], v[56:57], 0, v[18:19]
	global_load_dwordx4 v[42:45], v[64:65], off
	global_load_dwordx4 v[34:37], v[64:65], off offset:1024
	global_load_dwordx4 v[18:21], v[64:65], off offset:3072
	global_load_dwordx4 v[26:29], v[64:65], off offset:2048
	v_ashrrev_i32_e32 v53, 12, v66
	v_mul_hi_i32_i24_e32 v65, 0x6000, v53
	v_mul_i32_i24_e32 v64, 0x6000, v53
	v_lshl_add_u64 v[64:65], v[58:59], 0, v[64:65]
	v_add_co_u32_e32 v70, vcc, s12, v64
	global_load_dwordx4 v[82:85], v[64:65], off
	s_nop 0
	v_addc_co_u32_e32 v71, vcc, 0, v65, vcc
	global_load_dwordx4 v[72:75], v[70:71], off
	global_load_dwordx4 v[198:201], v[70:71], off offset:1024
	global_load_dwordx4 v[202:205], v[70:71], off offset:2048
	global_load_dwordx4 v[206:209], v[70:71], off offset:3072
	global_load_dwordx4 v[210:213], v[64:65], off offset:1024
	global_load_dwordx4 v[214:217], v[64:65], off offset:2048
	global_load_dwordx4 v[218:221], v[64:65], off offset:3072
	v_ashrrev_i32_e32 v86, 12, v68
	v_mul_hi_i32_i24_e32 v87, 0x6000, v86
	v_mul_i32_i24_e32 v86, 0x6000, v86
	v_lshl_add_u64 v[86:87], v[58:59], 0, v[86:87]
	global_load_dwordx4 v[222:225], v[86:87], off
	global_load_dwordx4 v[226:229], v[86:87], off offset:1024
	global_load_dwordx4 v[230:233], v[86:87], off offset:2048
	global_load_dwordx4 v[234:237], v[86:87], off offset:3072
	v_add_co_u32_e32 v86, vcc, 0x1000, v86
	s_nop 1
	v_addc_co_u32_e32 v87, vcc, 0, v87, vcc
	global_load_dwordx4 v[238:241], v[86:87], off
	global_load_dwordx4 v[242:245], v[86:87], off offset:1024
	global_load_dwordx4 v[246:249], v[86:87], off offset:2048
	global_load_dwordx4 v[250:253], v[86:87], off offset:3072
	v_lshlrev_b64 v[66:67], 11, v[66:67]
	v_ashrrev_i32_e32 v68, 12, v68
	s_waitcnt vmcnt(23)
	v_pk_mul_f32 v[70:71], v[48:49], v[48:49]
	v_pk_mul_f32 v[86:87], v[46:47], v[46:47]
	s_waitcnt vmcnt(22)
	v_pk_mul_f32 v[88:89], v[40:41], v[40:41]
	v_pk_mul_f32 v[90:91], v[38:39], v[38:39]
	v_pk_mov_b32 v[96:97], v[86:87], v[70:71] op_sel:[1,0]
	v_mov_b32_e32 v87, v71
	v_pk_mov_b32 v[70:71], v[90:91], v[88:89] op_sel:[1,0]
	v_mov_b32_e32 v91, v89
	s_waitcnt vmcnt(20)
	v_mul_f32_e32 v92, v31, v31
	v_mul_f32_e32 v94, v33, v33
	v_pk_add_f32 v[86:87], v[96:97], v[86:87]
	v_pk_add_f32 v[70:71], v[70:71], v[90:91]
	v_mul_f32_e32 v53, v22, v22
	v_mul_f32_e32 v63, v23, v23
	v_mul_f32_e32 v69, v24, v24
	v_mul_f32_e32 v100, v25, v25
	v_pk_fma_f32 v[88:89], v[30:31], v[30:31], v[92:93] op_sel_hi:[1,1,0]
	v_pk_fma_f32 v[92:93], v[32:33], v[32:33], v[94:95] op_sel_hi:[1,1,0]
	s_waitcnt vmcnt(19)
	v_pk_mul_f32 v[94:95], v[44:45], v[44:45]
	v_pk_mul_f32 v[96:97], v[42:43], v[42:43]
	s_waitcnt vmcnt(18)
	v_pk_mul_f32 v[90:91], v[36:37], v[36:37]
	v_pk_mul_f32 v[98:99], v[34:35], v[34:35]
	v_pk_add_f32 v[86:87], v[86:87], v[86:87] op_sel:[0,1] op_sel_hi:[1,0]
	v_pk_add_f32 v[70:71], v[70:71], v[70:71] op_sel:[0,1] op_sel_hi:[1,0]
	v_mov_b32_e32 v89, v69
	v_mov_b32_e32 v93, v100
	v_pk_mov_b32 v[104:105], v[96:97], v[94:95] op_sel:[1,0]
	v_mov_b32_e32 v97, v95
	v_pk_mov_b32 v[94:95], v[98:99], v[90:91] op_sel:[1,0]
	v_mov_b32_e32 v99, v91
	v_mov_b32_e32 v87, v53
	v_mov_b32_e32 v71, v63
	s_waitcnt vmcnt(17)
	v_mul_f32_e32 v101, v19, v19
	v_mul_f32_e32 v103, v20, v20
	s_waitcnt vmcnt(16)
	v_mul_f32_e32 v100, v27, v27
	v_mul_f32_e32 v102, v29, v29
	v_pk_add_f32 v[88:89], v[88:89], v[92:93]
	v_pk_add_f32 v[96:97], v[104:105], v[96:97]
	v_pk_add_f32 v[94:95], v[94:95], v[98:99]
	v_pk_add_f32 v[70:71], v[86:87], v[70:71]
	v_mul_f32_e32 v69, v18, v18
	v_mul_f32_e32 v106, v21, v21
	v_pk_fma_f32 v[90:91], v[26:27], v[26:27], v[100:101] op_sel_hi:[1,1,0]
	v_pk_fma_f32 v[92:93], v[28:29], v[28:29], v[102:103] op_sel_hi:[1,1,0]
	v_pk_add_f32 v[86:87], v[96:97], v[96:97] op_sel:[0,1] op_sel_hi:[1,0]
	v_pk_add_f32 v[94:95], v[94:95], v[94:95] op_sel:[0,1] op_sel_hi:[1,0]
	v_pk_add_f32 v[70:71], v[70:71], v[88:89]
	v_mov_b32_e32 v91, v103
	v_mov_b32_e32 v93, v106
	v_mov_b32_e32 v87, v69
	v_mov_b32_e32 v95, v101
	v_add_f32_e32 v53, v70, v71
	v_pk_add_f32 v[90:91], v[90:91], v[92:93]
	v_pk_add_f32 v[70:71], v[86:87], v[94:95]
	ds_bpermute_b32 v63, v76, v53
	v_pk_add_f32 v[70:71], v[70:71], v[90:91]
	s_waitcnt lgkmcnt(0)
	v_add_f32_e32 v53, v53, v63
	v_add_f32_e32 v69, v70, v71
	ds_bpermute_b32 v70, v76, v69
	ds_bpermute_b32 v71, v77, v53
	v_ashrrev_i32_e32 v63, 31, v62
	s_waitcnt lgkmcnt(1)
	v_add_f32_e32 v69, v69, v70
	ds_bpermute_b32 v86, v77, v69
	s_waitcnt lgkmcnt(1)
	v_add_f32_e32 v53, v53, v71
	ds_bpermute_b32 v87, v78, v53
	v_lshl_add_u64 v[70:71], v[60:61], 0, v[66:67]
	v_lshlrev_b64 v[66:67], 11, v[62:63]
	s_waitcnt lgkmcnt(1)
	v_add_f32_e32 v86, v69, v86
	ds_bpermute_b32 v88, v78, v86
	s_waitcnt lgkmcnt(1)
	v_add_f32_e32 v53, v53, v87
	ds_bpermute_b32 v63, v79, v53
	v_mul_hi_i32_i24_e32 v69, 0x6000, v68
	v_mul_i32_i24_e32 v68, 0x6000, v68
	s_waitcnt lgkmcnt(1)
	v_add_f32_e32 v86, v86, v88
	ds_bpermute_b32 v87, v79, v86
	s_waitcnt lgkmcnt(1)
	v_add_f32_e32 v53, v53, v63
	ds_bpermute_b32 v63, v80, v53
	v_lshl_add_u64 v[66:67], v[60:61], 0, v[66:67]
	v_lshl_add_u64 v[68:69], v[58:59], 0, v[68:69]
	s_waitcnt lgkmcnt(1)
	v_add_f32_e32 v88, v86, v87
	ds_bpermute_b32 v89, v80, v88
	s_waitcnt lgkmcnt(1)
	v_add_f32_e32 v53, v53, v63
	ds_bpermute_b32 v63, v81, v53
	s_waitcnt vmcnt(0)
	v_pk_add_f32 v[86:87], v[74:75], 1.0 op_sel_hi:[1,0]
	s_waitcnt lgkmcnt(1)
	v_add_f32_e32 v75, v88, v89
	ds_bpermute_b32 v90, v81, v75
	s_waitcnt lgkmcnt(1)
	v_add_f32_e32 v53, v53, v63
	v_fmamk_f32 v53, v53, 0x3a800000, v51
	v_rsq_f32_e32 v74, v53
	v_pk_add_f32 v[88:89], v[72:73], 1.0 op_sel_hi:[1,0]
	s_waitcnt lgkmcnt(0)
	v_add_f32_e32 v53, v75, v90
	v_fmamk_f32 v53, v53, 0x3a800000, v51
	v_rsq_f32_e32 v72, v53
	v_pk_mul_f32 v[48:49], v[48:49], v[74:75] op_sel_hi:[1,0]
	v_pk_mul_f32 v[46:47], v[46:47], v[74:75] op_sel_hi:[1,0]
	v_pk_mul_f32 v[48:49], v[4:5], v[48:49]
	v_pk_mul_f32 v[46:47], v[2:3], v[46:47]
	v_pk_fma_f32 v[48:49], v[86:87], v[48:49], v[84:85]
	v_pk_fma_f32 v[46:47], v[88:89], v[46:47], v[82:83]
	v_mov_b32_e32 v73, v72
	v_cvt_pk_bf16_f32 v46, v46, v47
	v_cvt_pk_bf16_f32 v47, v48, v49
	global_store_dwordx2 v[70:71], v[46:47], off
	s_and_saveexec_b64 s[10:11], s[0:1]
	s_cbranch_execz .LBB0_141
	v_add_co_u32_e32 v86, vcc, 0x1000, v68
	v_pk_mul_f32 v[42:43], v[42:43], v[72:73]
	s_nop 0
	v_addc_co_u32_e32 v87, vcc, 0, v69, vcc
	v_pk_mov_b32 v[46:47], v[238:239], v[238:239] op_sel:[0,1]
	v_pk_mov_b32 v[48:49], v[240:241], v[240:241] op_sel:[0,1]
	v_pk_mov_b32 v[82:83], v[222:223], v[222:223] op_sel:[0,1]
	v_pk_mov_b32 v[84:85], v[224:225], v[224:225] op_sel:[0,1]
	v_mov_b32_e32 v86, v72
	v_mov_b32_e32 v87, v72
	v_pk_mul_f32 v[44:45], v[44:45], v[86:87]
	v_pk_mul_f32 v[42:43], v[2:3], v[42:43]
	v_pk_mul_f32 v[44:45], v[4:5], v[44:45]
	v_pk_add_f32 v[48:49], v[48:49], 1.0 op_sel_hi:[1,0]
	v_pk_add_f32 v[46:47], v[46:47], 1.0 op_sel_hi:[1,0]
	v_pk_fma_f32 v[44:45], v[44:45], v[48:49], v[84:85]
	v_pk_fma_f32 v[42:43], v[42:43], v[46:47], v[82:83]
	s_nop 0
	v_cvt_pk_bf16_f32 v42, v42, v43
	v_cvt_pk_bf16_f32 v43, v44, v45
	global_store_dwordx2 v[66:67], v[42:43], off
.LBB0_141:
	s_or_b64 exec, exec, s[10:11]
	v_add_co_u32_e32 v42, vcc, 0x1000, v64
	v_mov_b32_e32 v75, v74
	s_nop 0
	v_addc_co_u32_e32 v43, vcc, 0, v65, vcc
	v_pk_mov_b32 v[44:45], v[198:199], v[198:199] op_sel:[0,1]
	v_pk_mov_b32 v[46:47], v[200:201], v[200:201] op_sel:[0,1]
	v_pk_mov_b32 v[82:83], v[210:211], v[210:211] op_sel:[0,1]
	v_pk_mov_b32 v[84:85], v[212:213], v[212:213] op_sel:[0,1]
	v_mov_b32_e32 v42, v74
	v_mov_b32_e32 v43, v74
	v_pk_mul_f32 v[40:41], v[40:41], v[42:43]
	v_pk_mul_f32 v[38:39], v[38:39], v[74:75]
	v_pk_mul_f32 v[40:41], v[8:9], v[40:41]
	v_pk_mul_f32 v[38:39], v[6:7], v[38:39]
	v_pk_add_f32 v[46:47], v[46:47], 1.0 op_sel_hi:[1,0]
	v_pk_add_f32 v[44:45], v[44:45], 1.0 op_sel_hi:[1,0]
	v_pk_fma_f32 v[40:41], v[40:41], v[46:47], v[84:85]
	v_pk_fma_f32 v[38:39], v[38:39], v[44:45], v[82:83]
	s_nop 0
	v_cvt_pk_bf16_f32 v38, v38, v39
	v_cvt_pk_bf16_f32 v39, v40, v41
	global_store_dwordx2 v[70:71], v[38:39], off offset:512
	s_and_saveexec_b64 s[10:11], s[0:1]
	s_cbranch_execz .LBB0_143
	v_add_co_u32_e32 v48, vcc, 0x1000, v68
	v_pk_mul_f32 v[34:35], v[34:35], v[72:73]
	s_nop 0
	v_addc_co_u32_e32 v49, vcc, 0, v69, vcc
	v_pk_mov_b32 v[38:39], v[242:243], v[242:243] op_sel:[0,1]
	v_pk_mov_b32 v[40:41], v[244:245], v[244:245] op_sel:[0,1]
	v_pk_mov_b32 v[44:45], v[226:227], v[226:227] op_sel:[0,1]
	v_pk_mov_b32 v[46:47], v[228:229], v[228:229] op_sel:[0,1]
	v_mov_b32_e32 v48, v72
	v_mov_b32_e32 v49, v72
	v_pk_mul_f32 v[36:37], v[36:37], v[48:49]
	v_pk_mul_f32 v[34:35], v[6:7], v[34:35]
	v_pk_mul_f32 v[36:37], v[8:9], v[36:37]
	v_pk_add_f32 v[40:41], v[40:41], 1.0 op_sel_hi:[1,0]
	v_pk_add_f32 v[38:39], v[38:39], 1.0 op_sel_hi:[1,0]
	v_pk_fma_f32 v[36:37], v[36:37], v[40:41], v[46:47]
	v_pk_fma_f32 v[34:35], v[34:35], v[38:39], v[44:45]
	s_nop 0
	v_cvt_pk_bf16_f32 v34, v34, v35
	v_cvt_pk_bf16_f32 v35, v36, v37
	global_store_dwordx2 v[66:67], v[34:35], off offset:512
.LBB0_143:
	s_or_b64 exec, exec, s[10:11]
	v_add_co_u32_e32 v44, vcc, 0x1000, v64
	v_pk_mul_f32 v[32:33], v[32:33], v[42:43]
	s_nop 0
	v_addc_co_u32_e32 v45, vcc, 0, v65, vcc
	v_pk_mov_b32 v[34:35], v[202:203], v[202:203] op_sel:[0,1]
	v_pk_mov_b32 v[36:37], v[204:205], v[204:205] op_sel:[0,1]
	v_pk_mov_b32 v[38:39], v[214:215], v[214:215] op_sel:[0,1]
	v_pk_mov_b32 v[40:41], v[216:217], v[216:217] op_sel:[0,1]
	v_pk_mul_f32 v[30:31], v[30:31], v[74:75]
	v_pk_mul_f32 v[32:33], v[12:13], v[32:33]
	v_pk_mul_f32 v[30:31], v[10:11], v[30:31]
	v_pk_add_f32 v[36:37], v[36:37], 1.0 op_sel_hi:[1,0]
	v_pk_add_f32 v[34:35], v[34:35], 1.0 op_sel_hi:[1,0]
	v_pk_fma_f32 v[32:33], v[32:33], v[36:37], v[40:41]
	v_pk_fma_f32 v[30:31], v[30:31], v[34:35], v[38:39]
	s_nop 0
	v_cvt_pk_bf16_f32 v30, v30, v31
	v_cvt_pk_bf16_f32 v31, v32, v33
	global_store_dwordx2 v[70:71], v[30:31], off offset:1024
	s_and_saveexec_b64 s[10:11], s[0:1]
	s_cbranch_execz .LBB0_145
	v_add_co_u32_e32 v38, vcc, 0x1000, v68
	v_pk_mul_f32 v[26:27], v[26:27], v[72:73]
	s_nop 0
	v_addc_co_u32_e32 v39, vcc, 0, v69, vcc
	v_pk_mov_b32 v[30:31], v[246:247], v[246:247] op_sel:[0,1]
	v_pk_mov_b32 v[32:33], v[248:249], v[248:249] op_sel:[0,1]
	v_pk_mov_b32 v[34:35], v[230:231], v[230:231] op_sel:[0,1]
	v_pk_mov_b32 v[36:37], v[232:233], v[232:233] op_sel:[0,1]
	v_mov_b32_e32 v38, v72
	v_mov_b32_e32 v39, v72
	v_pk_mul_f32 v[28:29], v[28:29], v[38:39]
	v_pk_mul_f32 v[26:27], v[10:11], v[26:27]
	v_pk_mul_f32 v[28:29], v[12:13], v[28:29]
	v_pk_add_f32 v[32:33], v[32:33], 1.0 op_sel_hi:[1,0]
	v_pk_add_f32 v[30:31], v[30:31], 1.0 op_sel_hi:[1,0]
	v_pk_fma_f32 v[28:29], v[28:29], v[32:33], v[36:37]
	v_pk_fma_f32 v[26:27], v[26:27], v[30:31], v[34:35]
	s_nop 0
	v_cvt_pk_bf16_f32 v26, v26, v27
	v_cvt_pk_bf16_f32 v27, v28, v29
	global_store_dwordx2 v[66:67], v[26:27], off offset:1024
.LBB0_145:
	s_or_b64 exec, exec, s[10:11]
	v_add_co_u32_e32 v34, vcc, 0x1000, v64
	v_pk_mul_f32 v[22:23], v[22:23], v[74:75]
	s_nop 0
	v_addc_co_u32_e32 v35, vcc, 0, v65, vcc
	v_pk_mov_b32 v[26:27], v[206:207], v[206:207] op_sel:[0,1]
	v_pk_mov_b32 v[28:29], v[208:209], v[208:209] op_sel:[0,1]
	v_pk_mov_b32 v[30:31], v[218:219], v[218:219] op_sel:[0,1]
	v_pk_mov_b32 v[32:33], v[220:221], v[220:221] op_sel:[0,1]
	v_mov_b32_e32 v34, v74
	v_mov_b32_e32 v35, v74
	v_pk_mul_f32 v[24:25], v[24:25], v[34:35]
	v_pk_mul_f32 v[22:23], v[14:15], v[22:23]
	v_pk_mul_f32 v[24:25], v[16:17], v[24:25]
	v_pk_add_f32 v[28:29], v[28:29], 1.0 op_sel_hi:[1,0]
	v_pk_add_f32 v[26:27], v[26:27], 1.0 op_sel_hi:[1,0]
	v_pk_fma_f32 v[24:25], v[24:25], v[28:29], v[32:33]
	v_pk_fma_f32 v[22:23], v[22:23], v[26:27], v[30:31]
	s_nop 0
	v_cvt_pk_bf16_f32 v22, v22, v23
	v_cvt_pk_bf16_f32 v23, v24, v25
	global_store_dwordx2 v[70:71], v[22:23], off offset:1536
	s_and_saveexec_b64 s[10:11], s[0:1]
	s_cbranch_execz .LBB0_138
	v_add_co_u32_e32 v30, vcc, 0x1000, v68
	v_pk_mul_f32 v[18:19], v[18:19], v[72:73]
	s_nop 0
	v_addc_co_u32_e32 v31, vcc, 0, v69, vcc
	v_pk_mov_b32 v[22:23], v[250:251], v[250:251] op_sel:[0,1]
	v_pk_mov_b32 v[24:25], v[252:253], v[252:253] op_sel:[0,1]
	v_pk_mov_b32 v[26:27], v[234:235], v[234:235] op_sel:[0,1]
	v_pk_mov_b32 v[28:29], v[236:237], v[236:237] op_sel:[0,1]
	v_mov_b32_e32 v30, v72
	v_mov_b32_e32 v31, v72
	v_pk_mul_f32 v[20:21], v[20:21], v[30:31]
	v_pk_mul_f32 v[18:19], v[14:15], v[18:19]
	v_pk_mul_f32 v[20:21], v[16:17], v[20:21]
	v_pk_add_f32 v[24:25], v[24:25], 1.0 op_sel_hi:[1,0]
	v_pk_add_f32 v[22:23], v[22:23], 1.0 op_sel_hi:[1,0]
	v_pk_fma_f32 v[20:21], v[20:21], v[24:25], v[28:29]
	v_pk_fma_f32 v[18:19], v[18:19], v[22:23], v[26:27]
	s_nop 0
	v_cvt_pk_bf16_f32 v18, v18, v19
	v_cvt_pk_bf16_f32 v19, v20, v21
	global_store_dwordx2 v[66:67], v[18:19], off offset:1536
	s_branch .LBB0_138
